# combination on the shared-B kernel: lean A pointers in the Hyena K loop + S4 transpose load remap + Hyena ticket prefetch
# baseline (speedup 1.0000x reference)
; DI void hyena_item_lat(const Params& p, int l, int it) {
;     ...
;   const int c = it >> 2, f = l, L = 2048, posoff = CTXL;
;   const int tt0 = (it & 3) * 512 + w * 128;
;   const u16* R0 = WSP(const u16, OFF_RF) + ((size_t)(f * 256 + c) * 2) * RSTR;
;   const u16* R1 = R0 + RSTR;
;   const u16* UT = WSP(const u16, OFF_UT);
;   const int l16 = lane & 15, kg = lane >> 4;
;   f32x4 acc[8];
; #pragma unroll
;   for (int i = 0; i < 8; ++i) acc[i] = (f32x4){0.f, 0.f, 0.f, 0.f};
;   const u16* ub = UT + ((size_t)(c * 16 + l16)) * TPB + posoff + kg * 8;
;   const u16* rsel = (l16 & 1) ? (R1 - 1) : R0;
;   const int nb = L - (tt0 + l16) + kg * 8;
;   union AF { u32 u[4]; bf16x8 v; };
;   AF a[8];
;     ...
; #pragma unroll
;   for (int i = 2; i < 8; ++i) HY_LOADA(a[i], nb - 16 * i)
.LBB0_1137:
	s_andn2_b64 vcc, exec, s[34:35]
	s_cbranch_vccnz .LBB0_1141
	v_cmp_eq_u32_e64 s[38:39], 0, v218
	s_and_saveexec_b64 s[36:37], s[38:39]
	v_mov_b32_e32 v120, 1
	global_atomic_add v120, v173, v120, s[0:1] sc0
	s_mov_b64 exec, s[36:37]
	s_mov_b32 s32, 1
	s_ashr_i32 s34, s13, 2
	v_mov_b32_e32 v0, v218
	v_mov_b32_e32 v1, v218
	s_add_i32 s36, s34, s42
	s_lshl_b32 s13, s13, 9
	s_ashr_i32 s37, s36, 31
	s_mul_i32 s38, s36, 0x4040
	v_readlane_b32 s16, v254, 47
	v_lshlrev_b32_e32 v1, 1, v1
	s_mul_hi_i32 s35, s36, 0x4040
	v_readlane_b32 s17, v254, 48
	s_add_u32 s38, s16, s38
	v_and_b32_e32 v1, 0xffffff80, v1
	s_addc_u32 s39, s17, s35
	s_and_b32 s13, s13, 0x600
	v_add_u32_e32 v63, s13, v1
	v_and_b32_e32 v62, 15, v0
	v_bfe_u32 v64, v0, 4, 2
	v_bfe_i32 v0, v0, 0, 1
	v_lshlrev_b32_e32 v1, 3, v64
	v_and_b32_e32 v172, 0x201e, v0
	v_or_b32_e32 v0, v63, v62
	v_sub_u32_e32 v58, v1, v0
	v_lshl_add_u64 v[56:57], s[38:39], 0, v[172:173]
	v_ashrrev_i32_e32 v59, 31, v58
	v_lshl_add_u64 v[0:1], v[58:59], 1, v[56:57]
	global_load_dwordx4 v[40:43], v[0:1], off offset:4032
	global_load_dwordx4 v[44:47], v[0:1], off offset:4000
	global_load_dwordx4 v[32:35], v[0:1], off offset:3968
	global_load_dwordx4 v[36:39], v[0:1], off offset:3936
	global_load_dwordx4 v[48:51], v[0:1], off offset:3904
	global_load_dwordx4 v[52:55], v[0:1], off offset:3872
	s_lshl_b32 s35, s34, 4
	v_or_b32_e32 v59, s35, v62
	v_mad_i64_i32 v[0:1], s[38:39], v59, s9, 0
	v_readlane_b32 s16, v255, 56
	v_lshl_or_b32 v0, v64, 4, v0
	v_readlane_b32 s17, v255, 57
	v_mov_b32_e32 v28, 0
	s_mov_b64 s[46:47], s[20:21]
	s_movk_i32 s13, 0xff80
	v_lshl_add_u64 v[60:61], s[16:17], 0, v[0:1]
	v_mov_b32_e32 v29, v28
	v_mov_b32_e32 v30, v28
	v_mov_b32_e32 v31, v28
	v_mov_b32_e32 v24, v28
	v_mov_b32_e32 v25, v28
	v_mov_b32_e32 v26, v28
	v_mov_b32_e32 v27, v28
	v_mov_b32_e32 v20, v28
	v_mov_b32_e32 v21, v28
	v_mov_b32_e32 v22, v28
	v_mov_b32_e32 v23, v28
	v_mov_b32_e32 v16, v28
	v_mov_b32_e32 v17, v28
	v_mov_b32_e32 v18, v28
	v_mov_b32_e32 v19, v28
	v_mov_b32_e32 v12, v28
	v_mov_b32_e32 v13, v28
	v_mov_b32_e32 v14, v28
	v_mov_b32_e32 v15, v28
	v_mov_b32_e32 v8, v28
	v_mov_b32_e32 v9, v28
	v_mov_b32_e32 v10, v28
	v_mov_b32_e32 v11, v28
	v_mov_b32_e32 v4, v28
	v_mov_b32_e32 v5, v28
	v_mov_b32_e32 v6, v28
	v_mov_b32_e32 v7, v28
	v_mov_b32_e32 v0, v28
	v_mov_b32_e32 v1, v28
	v_mov_b32_e32 v2, v28
	v_mov_b32_e32 v3, v28
	v_and_b32_e32 v92, 0xc0, v218
	v_mov_b32_e32 v93, 0
	v_lshlrev_b32_e32 v94, 4, v218
	v_and_b32_e32 v95, 63, v218
	v_lshl_add_u64 v[90:91], v[92:93], 0, v[60:61]
	v_lshlrev_b32_e32 v95, 4, v95
	global_load_dwordx4 v[82:85], v[90:91], off offset:-192
	v_add_u32_e32 v78, 0x800, v58
	v_add_u32_e32 v80, 0x7f0, v58
	v_ashrrev_i32_e32 v79, 31, v78
	v_ashrrev_i32_e32 v81, 31, v80
	v_lshl_add_u64 v[78:79], v[78:79], 1, v[56:57]
	v_lshl_add_u64 v[80:81], v[80:81], 1, v[56:57]
